# GEMM-up epilogue: row-index compares in 32 bits (operands are sign-extended 32-bit values)
# speedup vs baseline: 1.0001x; 1.0001x over previous
; #define UFOR(v, n) _Pragma("unroll") for (int v = 0; v < (n); ++v)
; __device__ __forceinline__ unsigned pk2(float a, float b) { return (unsigned)f2bf(a) | ((unsigned)f2bf(b) << 16); }
; __device__ __forceinline__ float lo2f(unsigned u) { return __uint_as_float(u << 16); }
; __device__ __forceinline__ float hi2f(unsigned u) { return __uint_as_float(u & 0xffff0000u); }
; __device__ __forceinline__ float siluf_(float x) { return x / (1.f + __expf(-x)); }
; template <int EPI, int K, int KL> ...
;     ...
;       for (int q = 0; q < 16; ++q) {
;         const int lr = lr0 + q;
;         const int lrn = lr < 255 ? lr + 1 : 255;
;         const uint2 a = *(const uint2*)(U + lrn * 256 + c4), b = *(const uint2*)(U + lrn * 256 + 128 + c4);
;         ng[0] = lo2f(a.x); ng[1] = hi2f(a.x); ng[2] = lo2f(a.y); ng[3] = hi2f(a.y);
;         nv[0] = lo2f(b.x); nv[1] = hi2f(b.x); nv[2] = lo2f(b.y); nv[3] = hi2f(b.y);
;         const long gr = brow + lr;
;         const bool valid = (gr >= seq0) && (gr < seq1) && (lr >= 1 || gr == seq0) && (lr <= 254 || gr == seq1 - 1);
;         if (valid) {
;           const float mp = (gr - 1 >= seq0) ? 1.f : 0.f, mn = (gr + 1 < seq1) ? 1.f : 0.f;
;           float o[4];
;           UFOR(x, 4) {
;             const float g = wg[x][0] * pg[x] * mp + wg[x][1] * cgv[x] + wg[x][2] * ng[x] * mn;
;             const float v = wv[x][0] * pvv[x] * mp + wv[x][1] * cv[x] + wv[x][2] * nv[x] * mn;
;             o[x] = siluf_(g) * v;
;           }
;           uint2 pk; pk.x = pk2(o[0], o[1]); pk.y = pk2(o[2], o[3]);
;           *(uint2*)(e.h2 + (size_t)gr * DFF + gc) = pk;
;         }
.LBB0_1112:
	v_lshl_add_u64 v[52:53], v[132:133], 0, s[58:59]
	v_min_i32_e32 v36, 0xfe, v52
	v_lshl_add_u32 v36, v36, 9, v64
	v_lshl_add_u64 v[54:55], v[28:29], 0, s[58:59]
	ds_read2_b64 v[40:43], v36 offset0:64 offset1:96
	v_cmp_le_i32_e32 vcc, s50, v54
	v_cmp_gt_i32_e64 s[42:43], s52, v54
	s_and_b64 s[62:63], vcc, s[42:43]
	v_cmp_lt_i32_e32 vcc, 0, v52
	v_cmp_eq_u32_e64 s[42:43], s58, v10
	s_or_b64 s[42:43], vcc, s[42:43]
	s_and_b64 s[62:63], s[62:63], s[42:43]
	v_cmp_gt_i32_e32 vcc, s27, v52
	v_cmp_eq_u32_e64 s[42:43], s58, v32
	s_or_b64 s[42:43], vcc, s[42:43]
	s_waitcnt lgkmcnt(0)
	v_lshlrev_b32_e32 v36, 16, v40
	v_lshlrev_b32_e32 v37, 16, v41
	v_and_b32_e32 v39, 0xffff0000, v41
	v_and_b32_e32 v38, 0xffff0000, v40
	v_lshlrev_b32_e32 v40, 16, v42
	v_lshlrev_b32_e32 v41, 16, v43
	v_and_b32_e32 v43, 0xffff0000, v43
	v_and_b32_e32 v42, 0xffff0000, v42
	s_and_b64 s[62:63], s[62:63], s[42:43]
	s_and_saveexec_b64 s[42:43], s[62:63]
	s_cbranch_execz .LBB0_1114
	v_cmp_lt_i32_e32 vcc, s50, v54
	v_pk_mul_f32 v[58:59], v[12:13], v[58:59]
	v_pk_mul_f32 v[56:57], v[22:23], v[56:57]
	v_cndmask_b32_e64 v66, 0, 1.0, vcc
	v_cmp_gt_i32_e32 vcc, s56, v54
	v_pk_mul_f32 v[58:59], v[58:59], v[66:67] op_sel_hi:[1,0]
	v_pk_mul_f32 v[70:71], v[14:15], v[36:37]
	v_cndmask_b32_e64 v68, 0, 1.0, vcc
	v_pk_fma_f32 v[58:59], v[0:1], v[46:47], v[58:59]
	v_pk_mul_f32 v[56:57], v[56:57], v[66:67] op_sel_hi:[1,0]
	v_pk_mul_f32 v[74:75], v[20:21], v[38:39]
	v_pk_fma_f32 v[58:59], v[70:71], v[68:69], v[58:59] op_sel_hi:[1,0,1]
	v_pk_fma_f32 v[56:57], v[8:9], v[44:45], v[56:57]
	v_mul_f32_e32 v53, 0xbfb8aa3b, v58
	v_pk_fma_f32 v[56:57], v[74:75], v[68:69], v[56:57] op_sel_hi:[1,0,1]
	v_exp_f32_e32 v70, v53
	v_mul_f32_e32 v53, 0xbfb8aa3b, v56
	v_exp_f32_e32 v74, v53
	v_mul_f32_e32 v53, 0xbfb8aa3b, v59
	v_exp_f32_e32 v71, v53
	v_pk_mul_f32 v[62:63], v[4:5], v[62:63]
	v_pk_mul_f32 v[72:73], v[6:7], v[40:41]
	v_pk_mul_f32 v[62:63], v[62:63], v[66:67] op_sel_hi:[1,0]
	v_pk_add_f32 v[70:71], v[70:71], 1.0 op_sel_hi:[1,0]
	v_pk_fma_f32 v[62:63], v[24:25], v[50:51], v[62:63]
	v_pk_fma_f32 v[62:63], v[68:69], v[72:73], v[62:63] op_sel_hi:[0,1,1]
	v_pk_mul_f32 v[60:61], v[18:19], v[60:61]
	v_pk_mul_f32 v[76:77], v[2:3], v[42:43]
	s_nop 0
	v_div_scale_f32 v80, vcc, v70, v70, v58
	v_div_scale_f32 v81, vcc, v71, v71, v59
	v_rcp_f32_e32 v82, v80
	v_rcp_f32_e32 v83, v81
	v_div_scale_f32 v86, s[62:63], v58, v70, v58
	v_div_scale_f32 v87, vcc, v59, v71, v59
	v_pk_fma_f32 v[84:85], v[80:81], v[82:83], 1.0 op_sel_hi:[1,1,0] neg_lo:[1,0,0] neg_hi:[1,0,0]
	v_pk_fma_f32 v[82:83], v[84:85], v[82:83], v[82:83]
	v_pk_mul_f32 v[88:89], v[86:87], v[82:83]
	v_pk_fma_f32 v[84:85], v[80:81], v[88:89], v[86:87] neg_lo:[1,0,0] neg_hi:[1,0,0]
	v_pk_fma_f32 v[88:89], v[84:85], v[82:83], v[88:89]
	v_pk_fma_f32 v[84:85], v[80:81], v[88:89], v[86:87] neg_lo:[1,0,0] neg_hi:[1,0,0]
	v_div_fmas_f32 v85, v85, v83, v89
	s_mov_b64 vcc, s[62:63]
	s_nop 0
	v_div_fmas_f32 v84, v84, v82, v88
	v_div_fixup_f32 v59, v85, v71, v59
	v_div_fixup_f32 v58, v84, v70, v58
	v_mul_f32_e32 v53, 0xbfb8aa3b, v57
	v_exp_f32_e32 v75, v53
	v_pk_mul_f32 v[58:59], v[62:63], v[58:59]
	v_pk_mul_f32 v[60:61], v[60:61], v[66:67] op_sel_hi:[1,0]
	v_pk_add_f32 v[62:63], v[74:75], 1.0 op_sel_hi:[1,0]
	s_nop 0
	v_pk_fma_f32 v[60:61], v[16:17], v[48:49], v[60:61]
	v_pk_fma_f32 v[60:61], v[68:69], v[76:77], v[60:61] op_sel_hi:[0,1,1]
	s_nop 0
	v_div_scale_f32 v80, vcc, v62, v62, v56
	v_div_scale_f32 v81, vcc, v63, v63, v57
	v_rcp_f32_e32 v82, v80
	v_rcp_f32_e32 v83, v81
	v_div_scale_f32 v86, s[62:63], v56, v62, v56
	v_div_scale_f32 v87, vcc, v57, v63, v57
	v_pk_fma_f32 v[84:85], v[80:81], v[82:83], 1.0 op_sel_hi:[1,1,0] neg_lo:[1,0,0] neg_hi:[1,0,0]
	v_pk_fma_f32 v[82:83], v[84:85], v[82:83], v[82:83]
	v_pk_mul_f32 v[88:89], v[86:87], v[82:83]
	v_pk_fma_f32 v[84:85], v[80:81], v[88:89], v[86:87] neg_lo:[1,0,0] neg_hi:[1,0,0]
	v_pk_fma_f32 v[88:89], v[84:85], v[82:83], v[88:89]
	v_pk_fma_f32 v[84:85], v[80:81], v[88:89], v[86:87] neg_lo:[1,0,0] neg_hi:[1,0,0]
	v_div_fmas_f32 v85, v85, v83, v89
	s_mov_b64 vcc, s[62:63]
	s_nop 0
	v_div_fmas_f32 v84, v84, v82, v88
	v_div_fixup_f32 v57, v85, v63, v57
	v_div_fixup_f32 v56, v84, v62, v56
	v_pk_mul_f32 v[56:57], v[60:61], v[56:57]
	v_cvt_pk_bf16_f32 v56, v58, v56
	v_cvt_pk_bf16_f32 v57, v59, v57
	v_add_co_u32_e32 v58, vcc, 0xffffe000, v30
	s_nop 0
	v_addc_co_u32_e32 v59, vcc, -1, v31, vcc
	global_store_dwordx2 v[58:59], v[56:57], off offset:-3072
; #define UFOR(v, n) _Pragma("unroll") for (int v = 0; v < (n); ++v)
; __device__ __forceinline__ unsigned pk2(float a, float b) { return (unsigned)f2bf(a) | ((unsigned)f2bf(b) << 16); }
; __device__ __forceinline__ float lo2f(unsigned u) { return __uint_as_float(u << 16); }
; __device__ __forceinline__ float hi2f(unsigned u) { return __uint_as_float(u & 0xffff0000u); }
; __device__ __forceinline__ float siluf_(float x) { return x / (1.f + __expf(-x)); }
; template <int EPI, int K, int KL> ...
;     ...
;       for (int q = 0; q < 16; ++q) {
;         const int lr = lr0 + q;
;         const int lrn = lr < 255 ? lr + 1 : 255;
;         const uint2 a = *(const uint2*)(U + lrn * 256 + c4), b = *(const uint2*)(U + lrn * 256 + 128 + c4);
;         ng[0] = lo2f(a.x); ng[1] = hi2f(a.x); ng[2] = lo2f(a.y); ng[3] = hi2f(a.y);
;         nv[0] = lo2f(b.x); nv[1] = hi2f(b.x); nv[2] = lo2f(b.y); nv[3] = hi2f(b.y);
;         const long gr = brow + lr;
;         const bool valid = (gr >= seq0) && (gr < seq1) && (lr >= 1 || gr == seq0) && (lr <= 254 || gr == seq1 - 1);
;         if (valid) {
;           const float mp = (gr - 1 >= seq0) ? 1.f : 0.f, mn = (gr + 1 < seq1) ? 1.f : 0.f;
;           float o[4];
;           UFOR(x, 4) {
;             const float g = wg[x][0] * pg[x] * mp + wg[x][1] * cgv[x] + wg[x][2] * ng[x] * mn;
;             const float v = wv[x][0] * pvv[x] * mp + wv[x][1] * cv[x] + wv[x][2] * nv[x] * mn;
;             o[x] = siluf_(g) * v;
;           }
;           uint2 pk; pk.x = pk2(o[0], o[1]); pk.y = pk2(o[2], o[3]);
;           *(uint2*)(e.h2 + (size_t)gr * DFF + gc) = pk;
;         }
;         UFOR(x, 4) { pg[x] = cgv[x]; cgv[x] = ng[x]; pvv[x] = cv[x]; cv[x] = nv[x]; }
;       }
.LBB0_1114:
	s_or_b64 exec, exec, s[42:43]
	v_add_u32_e32 v62, 1, v52
	v_min_i32_e32 v52, 0xfe, v62
	v_lshl_add_u32 v52, v52, 9, v64
	v_lshl_add_u64 v[54:55], v[54:55], 0, 1
	ds_read2_b64 v[58:61], v52 offset0:64 offset1:96
	v_cmp_le_i32_e32 vcc, s50, v54
	v_cmp_gt_i32_e64 s[42:43], s52, v54
	s_and_b64 s[42:43], vcc, s[42:43]
	v_cmp_eq_u32_e32 vcc, s58, v26
	s_or_b64 s[62:63], s[40:41], vcc
	s_and_b64 s[62:63], s[42:43], s[62:63]
	v_cmp_gt_i32_e32 vcc, s27, v62
	v_cmp_eq_u32_e64 s[42:43], s58, v34
	s_or_b64 s[42:43], vcc, s[42:43]
	s_waitcnt lgkmcnt(0)
	v_lshlrev_b32_e32 v52, 16, v58
	v_lshlrev_b32_e32 v53, 16, v59
	v_and_b32_e32 v57, 0xffff0000, v59
	v_and_b32_e32 v56, 0xffff0000, v58
	v_lshlrev_b32_e32 v58, 16, v60
	v_lshlrev_b32_e32 v59, 16, v61
	v_and_b32_e32 v61, 0xffff0000, v61
	v_and_b32_e32 v60, 0xffff0000, v60
	s_and_b64 s[62:63], s[62:63], s[42:43]
	s_and_saveexec_b64 s[42:43], s[62:63]
	s_cbranch_execz .LBB0_1111
	v_cmp_lt_i32_e32 vcc, s50, v54
	v_pk_mul_f32 v[46:47], v[12:13], v[46:47]
	v_pk_mul_f32 v[66:67], v[14:15], v[52:53]
	v_cndmask_b32_e64 v62, 0, 1.0, vcc
	v_cmp_gt_i32_e32 vcc, s56, v54
	v_pk_mul_f32 v[46:47], v[46:47], v[62:63] op_sel_hi:[1,0]
	v_pk_mul_f32 v[44:45], v[22:23], v[44:45]
	v_cndmask_b32_e64 v54, 0, 1.0, vcc
	v_pk_fma_f32 v[46:47], v[0:1], v[36:37], v[46:47]
	v_pk_mul_f32 v[44:45], v[44:45], v[62:63] op_sel_hi:[1,0]
	v_pk_fma_f32 v[46:47], v[66:67], v[54:55], v[46:47] op_sel_hi:[1,0,1]
	v_pk_mul_f32 v[50:51], v[4:5], v[50:51]
	v_pk_mul_f32 v[70:71], v[20:21], v[56:57]
	v_mul_f32_e32 v55, 0xbfb8aa3b, v46
	v_pk_fma_f32 v[44:45], v[8:9], v[38:39], v[44:45]
	v_pk_mul_f32 v[50:51], v[50:51], v[62:63] op_sel_hi:[1,0]
	v_pk_fma_f32 v[44:45], v[70:71], v[54:55], v[44:45] op_sel_hi:[1,0,1]
	v_pk_mul_f32 v[68:69], v[6:7], v[58:59]
	v_exp_f32_e32 v66, v55
	v_mul_f32_e32 v55, 0xbfb8aa3b, v44
	v_pk_fma_f32 v[50:51], v[24:25], v[40:41], v[50:51]
	v_exp_f32_e32 v70, v55
	v_pk_fma_f32 v[50:51], v[54:55], v[68:69], v[50:51] op_sel_hi:[0,1,1]
	v_mul_f32_e32 v55, 0xbfb8aa3b, v47
	v_exp_f32_e32 v67, v55
	v_pk_mul_f32 v[48:49], v[18:19], v[48:49]
	v_pk_mul_f32 v[72:73], v[2:3], v[60:61]
	v_pk_add_f32 v[66:67], v[66:67], 1.0 op_sel_hi:[1,0]
	s_nop 0
	s_nop 0
	s_nop 0
	v_div_scale_f32 v80, vcc, v66, v66, v46
	v_div_scale_f32 v81, vcc, v67, v67, v47
	v_rcp_f32_e32 v82, v80
	v_rcp_f32_e32 v83, v81
	v_div_scale_f32 v86, s[62:63], v46, v66, v46
	v_div_scale_f32 v87, vcc, v47, v67, v47
	v_pk_fma_f32 v[84:85], v[80:81], v[82:83], 1.0 op_sel_hi:[1,1,0] neg_lo:[1,0,0] neg_hi:[1,0,0]
	v_pk_fma_f32 v[82:83], v[84:85], v[82:83], v[82:83]
	v_pk_mul_f32 v[88:89], v[86:87], v[82:83]
	v_pk_fma_f32 v[84:85], v[80:81], v[88:89], v[86:87] neg_lo:[1,0,0] neg_hi:[1,0,0]
	v_pk_fma_f32 v[88:89], v[84:85], v[82:83], v[88:89]
	v_pk_fma_f32 v[84:85], v[80:81], v[88:89], v[86:87] neg_lo:[1,0,0] neg_hi:[1,0,0]
	v_div_fmas_f32 v85, v85, v83, v89
	s_mov_b64 vcc, s[62:63]
	s_nop 0
	v_div_fmas_f32 v84, v84, v82, v88
	v_div_fixup_f32 v47, v85, v67, v47
	v_div_fixup_f32 v46, v84, v66, v46
	v_pk_mul_f32 v[46:47], v[50:51], v[46:47]
	v_mul_f32_e32 v50, 0xbfb8aa3b, v45
	v_exp_f32_e32 v71, v50
	v_pk_mul_f32 v[48:49], v[48:49], v[62:63] op_sel_hi:[1,0]
	v_pk_add_f32 v[50:51], v[70:71], 1.0 op_sel_hi:[1,0]
	v_pk_fma_f32 v[48:49], v[16:17], v[42:43], v[48:49]
	s_nop 0
	v_pk_fma_f32 v[48:49], v[54:55], v[72:73], v[48:49] op_sel_hi:[0,1,1]
	s_nop 0
	s_nop 0
	v_div_scale_f32 v80, vcc, v50, v50, v44
	v_div_scale_f32 v81, vcc, v51, v51, v45
	v_rcp_f32_e32 v82, v80
	v_rcp_f32_e32 v83, v81
	v_div_scale_f32 v86, s[62:63], v44, v50, v44
	v_div_scale_f32 v87, vcc, v45, v51, v45
	v_pk_fma_f32 v[84:85], v[80:81], v[82:83], 1.0 op_sel_hi:[1,1,0] neg_lo:[1,0,0] neg_hi:[1,0,0]
	v_pk_fma_f32 v[82:83], v[84:85], v[82:83], v[82:83]
	v_pk_mul_f32 v[88:89], v[86:87], v[82:83]
	v_pk_fma_f32 v[84:85], v[80:81], v[88:89], v[86:87] neg_lo:[1,0,0] neg_hi:[1,0,0]
	v_pk_fma_f32 v[88:89], v[84:85], v[82:83], v[88:89]
	v_pk_fma_f32 v[84:85], v[80:81], v[88:89], v[86:87] neg_lo:[1,0,0] neg_hi:[1,0,0]
	v_div_fmas_f32 v85, v85, v83, v89
	s_mov_b64 vcc, s[62:63]
	s_nop 0
	v_div_fmas_f32 v84, v84, v82, v88
	v_div_fixup_f32 v45, v85, v51, v45
	v_div_fixup_f32 v44, v84, v50, v44
	v_pk_mul_f32 v[44:45], v[48:49], v[44:45]
	v_cvt_pk_bf16_f32 v45, v47, v45
	v_cvt_pk_bf16_f32 v44, v46, v44
	global_store_dwordx2 v[30:31], v[44:45], off
	s_branch .LBB0_1111
